# scan staging waves: y=S r pass with LDS lane addresses formed once before the loop and the four masked row stores grouped behind one address
# baseline (speedup 1.0000x reference)
.LBB0_1049:
	s_and_b64 vcc, exec, s[0:1]
	s_cbranch_vccz .LBB0_1102
	s_ashr_i32 s0, s2, 5
	s_bfe_u32 s7, s2, 0x30002
	v_lshlrev_b32_e32 v2, 2, v169
	s_ashr_i32 s1, s0, 31
	s_mul_i32 s10, s0, 0x1c8e400
	v_lshl_or_b32 v28, s7, 6, v2
	v_mov_b32_e32 v29, 0
	s_mul_hi_i32 s11, s0, 0x1c8e400
	s_add_u32 s10, s38, s10
	v_lshlrev_b64 v[6:7], 2, v[28:29]
	s_addc_u32 s11, s39, s11
	v_lshlrev_b32_e32 v28, 1, v28
	v_lshl_add_u64 v[30:31], s[10:11], 0, v[28:29]
	s_mul_i32 s11, s0, 0x804000
	s_mul_hi_i32 s10, s0, 0x804000
	s_add_u32 s4, s4, s11
	s_addc_u32 s5, s5, s10
	v_lshl_add_u64 v[32:33], s[4:5], 0, v[28:29]
	s_add_u32 s4, s16, s11
	s_addc_u32 s5, s17, s10
	v_lshl_add_u64 v[34:35], s[4:5], 0, v[28:29]
	s_mul_i32 s5, s0, 0x40200
	s_mul_hi_i32 s4, s0, 0x40200
	s_add_u32 s5, s28, s5
	s_addc_u32 s4, s29, s4
	s_lshl_b32 s10, s7, 2
	s_add_u32 s5, s5, s10
	s_addc_u32 s4, s4, 0
	s_add_u32 s36, s5, 0xfd30000
	s_addc_u32 s37, s4, 0
	s_lshl_b64 s[0:1], s[0:1], 23
	s_add_u32 s0, s44, s0
	s_addc_u32 s1, s45, s1
	s_lshl_b32 s4, s7, 7
	s_add_u32 s0, s0, s4
	s_addc_u32 s1, s1, 0
	s_lshl_b32 s4, s6, 5
	s_add_u32 s0, s0, s4
	s_addc_u32 s1, s1, 0
	s_add_u32 s40, s28, 0xfdf3f00
	v_readlane_b32 s4, v255, 5
	s_addc_u32 s41, s29, 0
	s_lshl_b32 s35, s4, 2
	v_lshlrev_b32_e32 v28, 3, v166
	s_add_i32 s62, s35, -16
	v_lshl_add_u64 v[26:27], s[0:1], 0, v[28:29]
	v_or_b32_e32 v28, s62, v166
	s_movk_i32 s63, 0xe40
	v_mad_u64_u32 v[2:3], s[0:1], v28, s63, v[30:31]
	v_max_i32_e32 v4, 1, v28
	global_load_dwordx2 v[24:25], v[2:3], off
	global_load_dwordx2 v[50:51], v[2:3], off offset:1024
	global_load_dwordx2 v[52:53], v[2:3], off offset:2048
	v_add_u32_e32 v2, -1, v4
	v_mad_u64_u32 v[2:3], s[0:1], v2, s63, v[30:31]
	v_readlane_b32 s64, v255, 7
	global_load_dwordx2 v[54:55], v[2:3], off
	global_load_dwordx2 v[56:57], v[2:3], off offset:1024
	global_load_dwordx2 v[58:59], v[2:3], off offset:2048
	v_lshlrev_b64 v[2:3], 10, v[28:29]
	v_readlane_b32 s78, v255, 21
	v_readlane_b32 s79, v255, 22
	v_lshl_add_u64 v[4:5], v[32:33], 0, v[2:3]
	v_lshl_add_u64 v[2:3], v[34:35], 0, v[2:3]
	v_lshl_add_u64 v[18:19], s[78:79], 0, v[6:7]
	global_load_dwordx2 v[60:61], v[4:5], off
	global_load_dwordx2 v[62:63], v[2:3], off
	v_lshl_add_u64 v[10:11], s[46:47], 0, v[6:7]
	global_load_dwordx4 v[2:5], v[18:19], off
	v_lshl_add_u64 v[14:15], s[48:49], 0, v[6:7]
	global_load_dwordx4 v[6:9], v[18:19], off offset:2048
	v_add_co_u32_e32 v18, vcc, 0x1000, v18
	global_load_dwordx4 v[10:13], v[10:11], off
	s_nop 0
	global_load_dwordx4 v[14:17], v[14:15], off
	v_addc_co_u32_e32 v19, vcc, 0, v19, vcc
	global_load_dwordx4 v[18:21], v[18:19], off
	v_or_b32_e32 v36, s35, v166
	v_add_u32_e32 v23, -1, v36
	v_cmp_eq_u32_e32 vcc, 0, v28
	v_mov_b32_e32 v37, v29
	v_mad_u64_u32 v[42:43], s[0:1], v36, s63, v[30:31]
	v_mad_u64_u32 v[46:47], s[0:1], v23, s63, v[30:31]
	v_cndmask_b32_e64 v72, 1.0, 0, vcc
	v_lshlrev_b64 v[38:39], 10, v[36:37]
	v_lshlrev_b64 v[40:41], 5, v[28:29]
	s_add_i32 s0, s35, 16
	v_lshlrev_b64 v[36:37], 5, v[36:37]
	v_lshl_add_u64 v[48:49], v[32:33], 0, v[38:39]
	v_lshl_add_u64 v[64:65], v[34:35], 0, v[38:39]
	v_lshl_add_u64 v[38:39], s[36:37], 0, v[40:41]
	v_lshl_add_u64 v[66:67], s[36:37], 0, v[36:37]
	global_load_dwordx2 v[36:37], v[46:47], off
	global_load_dwordx2 v[44:45], v[46:47], off offset:1024
	s_nop 0
	global_load_dwordx2 v[46:47], v[46:47], off offset:2048
	s_nop 0
	global_load_dwordx2 v[48:49], v[48:49], off
	s_nop 0
	global_load_dword v86, v[38:39], off
	s_nop 0
	global_load_dwordx2 v[38:39], v[42:43], off
	global_load_dwordx2 v[40:41], v[42:43], off offset:1024
	s_nop 0
	global_load_dwordx2 v[42:43], v[42:43], off offset:2048
	s_cmp_eq_u32 s4, 4
	v_readlane_b32 s69, v255, 12
	s_cselect_b64 s[46:47], -1, 0
	v_readlane_b32 s70, v255, 13
	s_movk_i32 s6, 0x90
	s_add_i32 s69, s35, -15
	v_readlane_b32 s71, v255, 14
	s_add_i32 s70, s35, -14
	s_add_i32 s71, s35, -13
	v_readlane_b32 s65, v255, 8
	v_readlane_b32 s66, v255, 9
	v_readlane_b32 s67, v255, 10
	v_readlane_b32 s68, v255, 11
	v_readlane_b32 s72, v255, 15
	s_mov_b32 s57, 0
	v_cmp_eq_u32_e64 s[4:5], 0, v178
	s_sub_i32 s67, s3, 64
	s_lshl_b32 s68, s62, 7
	s_lshl_b32 s66, s69, 7
	s_lshl_b32 s65, s70, 7
	s_lshl_b32 s64, s71, 7
	s_mov_b32 s72, 0
	v_readlane_b32 s73, v255, 16
	v_readlane_b32 s74, v255, 17
	v_readlane_b32 s75, v255, 18
	v_readlane_b32 s76, v255, 19
	v_readlane_b32 s77, v255, 20
	s_waitcnt vmcnt(20)
	v_lshlrev_b32_e32 v68, 16, v24
	v_and_b32_e32 v69, 0xffff0000, v24
	s_waitcnt vmcnt(19)
	v_lshlrev_b32_e32 v74, 16, v50
	v_and_b32_e32 v75, 0xffff0000, v50
	v_lshlrev_b32_e32 v76, 16, v51
	v_and_b32_e32 v77, 0xffff0000, v51
	s_waitcnt vmcnt(18)
	v_lshlrev_b32_e32 v78, 16, v52
	v_and_b32_e32 v79, 0xffff0000, v52
	v_lshlrev_b32_e32 v80, 16, v53
	v_and_b32_e32 v81, 0xffff0000, v53
	s_waitcnt vmcnt(17)
	v_lshlrev_b32_e32 v50, 16, v54
	v_and_b32_e32 v51, 0xffff0000, v54
	v_lshlrev_b32_e32 v52, 16, v55
	v_and_b32_e32 v53, 0xffff0000, v55
	s_waitcnt vmcnt(16)
	v_lshlrev_b32_e32 v82, 16, v56
	v_and_b32_e32 v83, 0xffff0000, v56
	v_lshlrev_b32_e32 v54, 16, v57
	v_and_b32_e32 v55, 0xffff0000, v57
	v_xor_b32_e32 v57, 0x80000000, v69
	v_xor_b32_e32 v56, 0x80000000, v68
	v_lshlrev_b32_e32 v24, 16, v25
	v_and_b32_e32 v25, 0xffff0000, v25
	v_pk_fma_f32 v[50:51], v[72:73], v[50:51], v[56:57] op_sel_hi:[0,1,1]
	v_xor_b32_e32 v57, 0x80000000, v25
	v_xor_b32_e32 v56, 0x80000000, v24
	s_waitcnt vmcnt(12)
	v_pk_fma_f32 v[94:95], v[2:3], v[50:51], v[68:69]
	v_xor_b32_e32 v51, 0x80000000, v77
	v_xor_b32_e32 v50, 0x80000000, v76
	v_or_b32_e32 v68, s0, v166
	v_pk_fma_f32 v[52:53], v[72:73], v[52:53], v[56:57] op_sel_hi:[0,1,1]
	v_pk_fma_f32 v[96:97], v[72:73], v[54:55], v[50:51] op_sel_hi:[0,1,1]
	v_add_u32_e32 v50, -1, v68
	v_mad_u64_u32 v[54:55], s[0:1], v68, s63, v[30:31]
	v_lshlrev_b32_e32 v84, 16, v58
	v_and_b32_e32 v85, 0xffff0000, v58
	v_lshlrev_b32_e32 v88, 16, v59
	v_and_b32_e32 v89, 0xffff0000, v59
	v_lshlrev_b32_e32 v23, 16, v60
	v_and_b32_e32 v87, 0xffff0000, v60
	v_lshlrev_b32_e32 v104, 16, v61
	v_and_b32_e32 v105, 0xffff0000, v61
	v_lshlrev_b32_e32 v90, 16, v62
	v_and_b32_e32 v91, 0xffff0000, v62
	v_pk_fma_f32 v[24:25], v[4:5], v[52:53], v[24:25]
	v_mad_u64_u32 v[70:71], s[0:1], v50, s63, v[30:31]
	global_load_dwordx2 v[58:59], v[64:65], off
	global_load_dword v62, v[66:67], off
	global_load_dwordx2 v[50:51], v[54:55], off
	global_load_dwordx2 v[52:53], v[54:55], off offset:1024
	s_nop 0
	global_load_dwordx2 v[54:55], v[54:55], off offset:2048
	s_nop 0
	global_load_dwordx2 v[56:57], v[70:71], off
	global_load_dwordx2 v[60:61], v[70:71], off offset:1024
	global_load_dwordx2 v[64:65], v[70:71], off offset:2048
	v_mov_b32_e32 v69, v29
	v_lshlrev_b64 v[66:67], 10, v[68:69]
	v_lshl_add_u64 v[70:71], v[32:33], 0, v[66:67]
	v_lshl_add_u64 v[100:101], v[34:35], 0, v[66:67]
	v_lshlrev_b64 v[66:67], 5, v[68:69]
	v_lshl_add_u64 v[102:103], s[36:37], 0, v[66:67]
	global_load_dwordx2 v[66:67], v[70:71], off
	global_load_dwordx2 v[68:69], v[100:101], off
	s_nop 0
	global_load_dword v70, v[102:103], off
	v_xor_b32_e32 v99, 0x80000000, v75
	v_xor_b32_e32 v98, 0x80000000, v74
	v_pk_fma_f32 v[82:83], v[72:73], v[82:83], v[98:99] op_sel_hi:[0,1,1]
	v_mul_f32_e32 v23, 0xbfb8aa3b, v23
	s_waitcnt vmcnt(22)
	v_pk_fma_f32 v[98:99], v[6:7], v[82:83], v[74:75]
	v_exp_f32_e32 v82, v23
	v_mul_f32_e32 v23, 0xbfb8aa3b, v87
	v_xor_b32_e32 v75, 0x80000000, v79
	v_xor_b32_e32 v74, 0x80000000, v78
	v_exp_f32_e32 v83, v23
	v_mul_f32_e32 v23, 0xbfb8aa3b, v104
	v_pk_fma_f32 v[96:97], v[8:9], v[96:97], v[76:77]
	v_pk_fma_f32 v[74:75], v[72:73], v[84:85], v[74:75] op_sel_hi:[0,1,1]
	v_xor_b32_e32 v77, 0x80000000, v81
	v_xor_b32_e32 v76, 0x80000000, v80
	v_exp_f32_e32 v84, v23
	v_mul_f32_e32 v23, 0xbfb8aa3b, v105
	v_lshlrev_b32_e32 v92, 16, v63
	v_and_b32_e32 v93, 0xffff0000, v63
	v_pk_fma_f32 v[72:73], v[72:73], v[88:89], v[76:77] op_sel_hi:[0,1,1]
	v_exp_f32_e32 v85, v23
	s_movk_i32 s0, 0x500
	s_waitcnt vmcnt(19)
	v_pk_fma_f32 v[76:77], v[20:21], v[72:73], v[80:81]
	v_pk_add_f32 v[72:73], v[92:93], -1.0 op_sel_hi:[1,0]
	v_mul_lo_u32 v23, v28, s0
	v_pk_fma_f32 v[72:73], v[16:17], v[72:73], 1.0 op_sel_hi:[1,1,0]
	v_add_u32_e32 v23, 0, v23
	v_pk_mul_f32 v[80:81], v[96:97], v[72:73]
	v_lshl_add_u32 v73, v169, 4, v23
	ds_write_b128 v73, v[82:85]
	v_pk_mul_f32 v[82:83], v[12:13], v[96:97] neg_lo:[0,1] neg_hi:[0,1]
	v_pk_fma_f32 v[74:75], v[18:19], v[74:75], v[78:79]
	s_waitcnt vmcnt(14)
	v_pk_mul_f32 v[84:85], v[86:87], v[82:83] op_sel_hi:[0,1]
	v_pk_mul_f32 v[82:83], v[10:11], v[98:99] neg_lo:[0,1] neg_hi:[0,1]
	v_pk_add_f32 v[78:79], v[90:91], -1.0 op_sel_hi:[1,0]
	v_pk_mul_f32 v[82:83], v[86:87], v[82:83] op_sel_hi:[0,1]
	v_pk_fma_f32 v[78:79], v[14:15], v[78:79], 1.0 op_sel_hi:[1,1,0]
	ds_write_b128 v73, v[82:85] offset:256
	v_pk_mul_f32 v[84:85], v[84:85], v[92:93] neg_lo:[1,0] neg_hi:[1,0]
	v_pk_mul_f32 v[82:83], v[82:83], v[90:91] neg_lo:[1,0] neg_hi:[1,0]
	s_movk_i32 s0, 0xfb80
	v_pk_mul_f32 v[78:79], v[98:99], v[78:79]
	ds_write_b128 v73, v[82:85] offset:512
	ds_write_b128 v73, v[78:81] offset:768
	ds_write_b128 v73, v[74:77] offset:1024
	v_cvt_pk_bf16_f32 v77, v24, v25
	v_mul_lo_u32 v24, v28, s0
	v_cvt_pk_bf16_f32 v76, v94, v95
	v_add3_u32 v75, v23, v24, v22
	v_and_b32_e32 v22, 48, v0
	s_add_i32 s0, 0, 0x14000
	ds_write_b64 v75, v[76:77] offset:40960
	v_add_u32_e32 v76, s0, v22
	v_add_u32_e32 v63, 0, v22
	v_lshl_or_b32 v22, s62, 4, v169
	v_mul_lo_u32 v79, v22, s6
	v_lshl_or_b32 v22, s69, 4, v169
	v_mul_lo_u32 v74, v22, s6
	v_lshl_or_b32 v22, s70, 4, v169
	v_mul_lo_u32 v72, v22, s6
	v_lshl_or_b32 v22, s71, 4, v169
	v_cmp_eq_u32_e64 s[0:1], 0, v169
	v_add_u32_e32 v77, 48, v28
	v_or_b32_e32 v78, 64, v166
	v_mul_lo_u32 v71, v22, s6
	v_sub_u32_e32 v80, 0, v28
	v_add_u32_e32 v212, v76, v79
	v_add_u32_e32 v216, v63, v79
	v_add_u32_e32 v220, s68, v63
	v_add_u32_e32 v213, v76, v74
	v_add_u32_e32 v217, v63, v74
	v_add_u32_e32 v221, s66, v63
	v_add_u32_e32 v214, v76, v72
	v_add_u32_e32 v218, v63, v72
	v_add_u32_e32 v222, s65, v63
	v_add_u32_e32 v215, v76, v71
	v_add_u32_e32 v219, v63, v71
	v_add_u32_e32 v223, s64, v63
	s_waitcnt lgkmcnt(0)
	s_barrier
	s_branch .LBB0_1053

.LBB0_1066:
	s_or_b64 exec, exec, s[6:7]
	s_cmp_eq_u32 s72, 0
	s_cbranch_scc1 .LBB0_1076
	ds_read_b128 v[224:227], v212
	ds_read_b128 v[228:231], v212 offset:64
	ds_read_b128 v[232:235], v220 offset:43008
	ds_read_b128 v[236:239], v220 offset:43072
	s_waitcnt lgkmcnt(1)
	v_mfma_f32_16x16x32_bf16 v[244:247], v[224:227], v[232:235], 0
	s_waitcnt lgkmcnt(0)
	v_mfma_f32_16x16x32_bf16 v[244:247], v[228:231], v[236:239], v[244:247]
	ds_read_b128 v[180:183], v213
	ds_read_b128 v[184:187], v213 offset:64
	ds_read_b128 v[188:191], v221 offset:43008
	ds_read_b128 v[192:195], v221 offset:43072
	s_waitcnt lgkmcnt(1)
	v_mfma_f32_16x16x32_bf16 v[248:251], v[180:183], v[188:191], 0
	s_waitcnt lgkmcnt(0)
	v_mfma_f32_16x16x32_bf16 v[248:251], v[184:187], v[192:195], v[248:251]
	ds_read_b128 v[224:227], v214
	ds_read_b128 v[228:231], v214 offset:64
	ds_read_b128 v[232:235], v222 offset:43008
	ds_read_b128 v[236:239], v222 offset:43072
	s_waitcnt lgkmcnt(1)
	v_mfma_f32_16x16x32_bf16 v[196:199], v[224:227], v[232:235], 0
	s_waitcnt lgkmcnt(0)
	v_mfma_f32_16x16x32_bf16 v[196:199], v[228:231], v[236:239], v[196:199]
	ds_read_b128 v[180:183], v215
	ds_read_b128 v[184:187], v215 offset:64
	ds_read_b128 v[188:191], v223 offset:43008
	ds_read_b128 v[192:195], v223 offset:43072
	s_waitcnt lgkmcnt(1)
	v_mfma_f32_16x16x32_bf16 v[128:131], v[180:183], v[188:191], 0
	s_waitcnt lgkmcnt(0)
	v_mfma_f32_16x16x32_bf16 v[128:131], v[184:187], v[192:195], v[128:131]
	s_lshl_b32 s30, s72, 4
	s_add_i32 s30, s30, s62
	s_add_i32 s30, s30, -32
	s_mov_b32 s31, 0
	s_lshl_b64 s[30:31], s[30:31], 10
	s_and_saveexec_b64 s[6:7], s[0:1]
	s_cbranch_execz .Lyq1_skip
	v_lshl_add_u64 v[136:137], v[26:27], 0, s[30:31]
	v_cvt_pk_bf16_f32 v134, v244, v245
	v_cvt_pk_bf16_f32 v135, v246, v247
	global_store_dwordx2 v[136:137], v[134:135], off
	v_cvt_pk_bf16_f32 v134, v248, v249
	v_cvt_pk_bf16_f32 v135, v250, v251
	global_store_dwordx2 v[136:137], v[134:135], off offset:1024
	v_cvt_pk_bf16_f32 v134, v196, v197
	v_cvt_pk_bf16_f32 v135, v198, v199
	global_store_dwordx2 v[136:137], v[134:135], off offset:2048
	v_cvt_pk_bf16_f32 v134, v128, v129
	v_cvt_pk_bf16_f32 v135, v130, v131
	global_store_dwordx2 v[136:137], v[134:135], off offset:3072

.LBB0_1079:
	s_andn2_b64 vcc, exec, s[30:31]
	s_waitcnt lgkmcnt(0)
	s_barrier
	s_cbranch_vccnz .LBB0_1052
	s_lshl_b32 s11, s72, 4
	s_add_i32 s10, s62, s11
	s_cmp_eq_u32 s72, 0
	s_cbranch_scc1 .Lyq2_none
	ds_read_b128 v[224:227], v216 offset:45056
	ds_read_b128 v[228:231], v216 offset:45120
	ds_read_b128 v[232:235], v220 offset:40960
	ds_read_b128 v[236:239], v220 offset:41024
	s_waitcnt lgkmcnt(1)
	v_mfma_f32_16x16x32_bf16 v[244:247], v[224:227], v[232:235], 0
	s_waitcnt lgkmcnt(0)
	v_mfma_f32_16x16x32_bf16 v[244:247], v[228:231], v[236:239], v[244:247]
	ds_read_b128 v[180:183], v217 offset:45056
	ds_read_b128 v[184:187], v217 offset:45120
	ds_read_b128 v[188:191], v221 offset:40960
	ds_read_b128 v[192:195], v221 offset:41024
	s_waitcnt lgkmcnt(1)
	v_mfma_f32_16x16x32_bf16 v[248:251], v[180:183], v[188:191], 0
	s_waitcnt lgkmcnt(0)
	v_mfma_f32_16x16x32_bf16 v[248:251], v[184:187], v[192:195], v[248:251]
	ds_read_b128 v[224:227], v218 offset:45056
	ds_read_b128 v[228:231], v218 offset:45120
	ds_read_b128 v[232:235], v222 offset:40960
	ds_read_b128 v[236:239], v222 offset:41024
	s_waitcnt lgkmcnt(1)
	v_mfma_f32_16x16x32_bf16 v[196:199], v[224:227], v[232:235], 0
	s_waitcnt lgkmcnt(0)
	v_mfma_f32_16x16x32_bf16 v[196:199], v[228:231], v[236:239], v[196:199]
	ds_read_b128 v[180:183], v219 offset:45056
	ds_read_b128 v[184:187], v219 offset:45120
	ds_read_b128 v[188:191], v223 offset:40960
	ds_read_b128 v[192:195], v223 offset:41024
	s_waitcnt lgkmcnt(1)
	v_mfma_f32_16x16x32_bf16 v[128:131], v[180:183], v[188:191], 0
	s_waitcnt lgkmcnt(0)
	v_mfma_f32_16x16x32_bf16 v[128:131], v[184:187], v[192:195], v[128:131]
	s_lshl_b32 s30, s72, 4
	s_add_i32 s30, s30, s62
	s_add_i32 s30, s30, -16
	s_mov_b32 s31, 0
	s_lshl_b64 s[30:31], s[30:31], 10
	s_and_saveexec_b64 s[6:7], s[0:1]
	s_cbranch_execz .Lyq2_skip
	v_lshl_add_u64 v[136:137], v[26:27], 0, s[30:31]
	v_cvt_pk_bf16_f32 v134, v244, v245
	v_cvt_pk_bf16_f32 v135, v246, v247
	global_store_dwordx2 v[136:137], v[134:135], off
	v_cvt_pk_bf16_f32 v134, v248, v249
	v_cvt_pk_bf16_f32 v135, v250, v251
	global_store_dwordx2 v[136:137], v[134:135], off offset:1024
	v_cvt_pk_bf16_f32 v134, v196, v197
	v_cvt_pk_bf16_f32 v135, v198, v199
	global_store_dwordx2 v[136:137], v[134:135], off offset:2048
	v_cvt_pk_bf16_f32 v134, v128, v129
	v_cvt_pk_bf16_f32 v135, v130, v131
	global_store_dwordx2 v[136:137], v[134:135], off offset:3072

.Lyq2_none:
	s_cmpk_lg_i32 s72, 0x150
	s_cbranch_scc0 .LBB0_1090
.LBB0_1088:
	s_cmpk_gt_u32 s72, 0x1fe
	s_cbranch_scc1 .LBB0_1051
	s_branch .LBB0_1091
.LBB0_1090:
	s_waitcnt vmcnt(0)
	s_cmpk_gt_u32 s72, 0x1fe
	s_cbranch_scc1 .LBB0_1051
